# attention key loop: address arithmetic and the 15 K-fragment reads moved to the loop header in front of the V-tile DMA issue and lane-mask code
# speedup vs baseline: 1.0208x; 1.0026x over previous
; DI int kswz(int key) { return (((key >> 3) & 3) << 2) | (key & 3); }
; DI void attn_item(const Params& p, int l, bool isS, int b, int h, int cp, char* smem) {
;     ...
;   auto issue_v = [&](int kt) {
; #pragma unroll
;     for (int i = 0; i < 2; ++i)
;       __builtin_amdgcn_global_load_lds((const unsigned*)(Vg + (size_t)(vvd + i * 64) * vstride + kt * 64 + vgch * 8), (unsigned*)(Vs + (kt & 1) * 16384 + soff + i * 8192), 16, 0, 0);
;   };
;   auto qk_tile = [&](int kt, f32x4 (&st)[2][4]) {
;     const char* Kb = Ks + (kt & 1) * 16384;
;     bf16x8 kf[2][4][2];
; #pragma unroll
;     for (int mp = 0; mp < 2; ++mp)
; #pragma unroll
;       for (int mt = 0; mt < 4; ++mt) {
;         const int key = 32 * (mt >> 1) + 8 * (fr >> 2) + 4 * (mt & 1) + (fr & 3);
; #pragma unroll
;         for (int ks = 0; ks < 2; ++ks) kf[mp][mt][ks] = *(const bf16x8*)(Kb + key * 256 + (((mp * 8 + ks * 4 + fq) ^ kswz(key)) << 4));
;       }
.LBB0_1370:
	s_add_i32 s20, s34, 0x4000
	s_and_b32 s20, s20, 0x4000
	v_add_u32_e32 v248, s20, v151
	v_add_u32_e32 v170, v248, v146
	v_add_u32_e32 v171, v248, v147
	v_add_u32_e32 v242, v248, v148
	v_add_u32_e32 v243, v248, v149
	s_and_b32 s24, s34, 0x4000
	v_add_u32_e32 v249, s24, v150
	v_add_u32_e32 v244, v249, v137
	v_add_u32_e32 v245, v249, v145
	ds_read_b128 v[154:157], v170
	ds_read_b128 v[158:161], v171
	ds_read_b128 v[162:165], v170 offset:1024
	ds_read_b128 v[166:169], v171 offset:1024
	ds_read_b128 v[176:179], v170 offset:8192
	ds_read_b128 v[180:183], v171 offset:8192
	ds_read_b128 v[198:201], v170 offset:9216
	ds_read_b128 v[202:205], v171 offset:9216
	ds_read_b128 v[206:209], v242
	ds_read_b128 v[214:217], v243
	ds_read_b128 v[218:221], v242 offset:1024
	ds_read_b128 v[222:225], v243 offset:1024
	ds_read_b128 v[226:229], v242 offset:8192
	ds_read_b128 v[230:233], v243 offset:8192
	ds_read_b128 v[234:237], v242 offset:9216
	s_add_i32 s35, s30, 1
	s_cmp_ge_i32 s35, s9
	s_cbranch_scc1 .LBB0_1372
	s_add_i32 s20, s34, 0x4000
	s_and_b32 s20, s20, 0x4000
	v_add_u32_e32 v100, s20, v133
	v_add_u32_e32 v104, 0x8000, v100
	s_add_i32 s20, s11, 64
	v_add_u32_e32 v105, 0xa000, v100
	s_lshl_b64 s[28:29], s[20:21], 1
	v_readfirstlane_b32 s20, v104
	v_lshl_add_u64 v[102:103], v[138:139], 0, s[28:29]
	s_mov_b32 m0, s20
	v_readfirstlane_b32 s20, v105
	v_lshl_add_u64 v[100:101], v[140:141], 0, s[28:29]
	global_load_lds_dwordx4 v[102:103], off
	s_mov_b32 m0, s20
	s_nop 0
	global_load_lds_dwordx4 v[100:101], off

; #define MFMA16(a, b, c) __builtin_amdgcn_mfma_f32_16x16x32_bf16((a), (b), (c), 0, 0, 0)
; DI int kswz(int key) { return (((key >> 3) & 3) << 2) | (key & 3); }
; DI void attn_item(const Params& p, int l, bool isS, int b, int h, int cp, char* smem) {
;     ...
;   auto qk_tile = [&](int kt, f32x4 (&st)[2][4]) {
;     const char* Kb = Ks + (kt & 1) * 16384;
;     bf16x8 kf[2][4][2];
; #pragma unroll
;     for (int mp = 0; mp < 2; ++mp)
; #pragma unroll
;       for (int mt = 0; mt < 4; ++mt) {
;         const int key = 32 * (mt >> 1) + 8 * (fr >> 2) + 4 * (mt & 1) + (fr & 3);
; #pragma unroll
;         for (int ks = 0; ks < 2; ++ks) kf[mp][mt][ks] = *(const bf16x8*)(Kb + key * 256 + (((mp * 8 + ks * 4 + fq) ^ kswz(key)) << 4));
;       }
; #pragma unroll
;     for (int mp = 0; mp < 2; ++mp)
; #pragma unroll
;       for (int mt = 0; mt < 4; ++mt) {
;         f32x4 a = MFMA16(kf[mp][mt][0], qf[mp][0], (f32x4{0.f, 0.f, 0.f, 0.f}));
;         st[mp][mt] = MFMA16(kf[mp][mt][1], qf[mp][1], a);
;       }
;     if ((kt + 1) * 64 > klen) {
;       asm volatile("" ::: "memory");
; #pragma unroll
;       for (int mp = 0; mp < 2; ++mp)
; #pragma unroll
;         for (int mt = 0; mt < 4; ++mt)
; #pragma unroll
;           for (int j = 0; j < 4; ++j) {
;             const int key = kt * 64 + 32 * (mt >> 1) + 8 * fq + 4 * (mt & 1) + j;
;             if (key >= klen) st[mp][mt][j] = -INFINITY;
;           }
;     }
;     ...
;     auto pv_tile = [&]() {
;       const char* Vb = Vs + (j & 1) * 16384;
; #pragma unroll
;       for (int nh = 0; nh < 2; ++nh) {
;         bf16x8 vf[4][2];
; #pragma unroll
;         for (int n = 0; n < 4; ++n) {
;           const int vd = (nh * 4 + n) * 16 + fr;
; #pragma unroll
;           for (int s = 0; s < 2; ++s) vf[n][s] = *(const bf16x8*)(Vb + vd * 128 + (((s * 4 + fq) ^ ((vd >> 1) & 7)) << 4));
.LBB0_1376:
	s_andn2_saveexec_b64 s[28:29], s[28:29]
	s_cbranch_execz .LBB0_1386
	s_waitcnt lgkmcnt(13)
	v_mfma_f32_16x16x32_bf16 v[124:127], v[154:157], v[8:11], 0
	v_mfma_f32_16x16x32_bf16 v[124:127], v[158:161], v[4:7], v[124:127]
	ds_read_b128 v[238:241], v243 offset:9216
	s_waitcnt lgkmcnt(12)
	v_mfma_f32_16x16x32_bf16 v[120:123], v[162:165], v[8:11], 0
	v_mfma_f32_16x16x32_bf16 v[120:123], v[166:169], v[4:7], v[120:123]
	s_waitcnt lgkmcnt(10)
	v_mfma_f32_16x16x32_bf16 v[112:115], v[176:179], v[8:11], 0
	v_mfma_f32_16x16x32_bf16 v[112:115], v[180:183], v[4:7], v[112:115]
	s_waitcnt lgkmcnt(8)
	v_mfma_f32_16x16x32_bf16 v[116:119], v[198:201], v[8:11], 0
	v_mfma_f32_16x16x32_bf16 v[116:119], v[202:205], v[4:7], v[116:119]
	ds_read_b128 v[154:157], v244 offset:32768
	ds_read_b128 v[158:161], v245 offset:32768
	ds_read_b128 v[162:165], v244 offset:34816
	ds_read_b128 v[166:169], v245 offset:34816
	ds_read_b128 v[176:179], v244 offset:36864
	ds_read_b128 v[180:183], v245 offset:36864
	ds_read_b128 v[198:201], v244 offset:38912
	s_waitcnt lgkmcnt(13)
	v_mfma_f32_16x16x32_bf16 v[104:107], v[206:209], v[16:19], 0
	v_mfma_f32_16x16x32_bf16 v[104:107], v[214:217], v[12:15], v[104:107]
	ds_read_b128 v[202:205], v245 offset:38912
	s_waitcnt lgkmcnt(12)
	v_mfma_f32_16x16x32_bf16 v[108:111], v[218:221], v[16:19], 0
	v_mfma_f32_16x16x32_bf16 v[108:111], v[222:225], v[12:15], v[108:111]
	s_waitcnt lgkmcnt(10)
	v_mfma_f32_16x16x32_bf16 v[100:103], v[226:229], v[16:19], 0
	v_mfma_f32_16x16x32_bf16 v[100:103], v[230:233], v[12:15], v[100:103]
	s_waitcnt lgkmcnt(8)
	v_mfma_f32_16x16x32_bf16 v[128:131], v[234:237], v[16:19], 0
	v_mfma_f32_16x16x32_bf16 v[128:131], v[238:241], v[12:15], v[128:131]
	ds_read_b128 v[206:209], v244 offset:40960
	ds_read_b128 v[214:217], v245 offset:40960
	ds_read_b128 v[218:221], v244 offset:43008
	ds_read_b128 v[222:225], v245 offset:43008
	ds_read_b128 v[226:229], v244 offset:45056
	ds_read_b128 v[230:233], v245 offset:45056
	ds_read_b128 v[234:237], v244 offset:47104
	s_add_i32 s20, s11, 0x80
	s_cmp_le_i32 s20, s10
	s_cbranch_scc1 .Lat_nomask
	s_nop 7
	v_add_u32_e32 v246, s11, v132
	v_add_u32_e32 v247, 64, v246
	v_cmp_gt_i32_e64 s[38:39], s10, v247
	v_add_u32_e32 v247, 0x41, v246
	v_cmp_gt_i32_e64 s[40:41], s10, v247
	v_add_u32_e32 v247, 0x42, v246
	v_cmp_gt_i32_e64 s[42:43], s10, v247
	v_add_u32_e32 v247, 0x43, v246
	v_cmp_gt_i32_e64 s[44:45], s10, v247
	v_add_u32_e32 v247, 0x44, v246
	v_cmp_gt_i32_e64 s[46:47], s10, v247
	v_add_u32_e32 v247, 0x45, v246
	v_cmp_gt_i32_e64 s[48:49], s10, v247
	v_add_u32_e32 v247, 0x46, v246
	v_cmp_gt_i32_e64 s[50:51], s10, v247
	v_add_u32_e32 v247, 0x47, v246
	v_cmp_gt_i32_e64 s[52:53], s10, v247
	v_add_u32_e32 v247, 0x60, v246
	v_cmp_gt_i32_e64 s[54:55], s10, v247
	v_add_u32_e32 v247, 0x61, v246
	v_cmp_gt_i32_e64 s[56:57], s10, v247
	v_add_u32_e32 v247, 0x62, v246
	v_cmp_gt_i32_e64 s[58:59], s10, v247
	v_add_u32_e32 v247, 0x63, v246
	v_cmp_gt_i32_e64 s[60:61], s10, v247
	v_add_u32_e32 v247, 0x64, v246
	v_cmp_gt_i32_e64 s[62:63], s10, v247
	v_add_u32_e32 v247, 0x65, v246
	v_cmp_gt_i32_e64 s[64:65], s10, v247
	v_add_u32_e32 v247, 0x66, v246
	v_add_u32_e32 v246, 0x67, v246
	v_cmp_gt_i32_e64 s[66:67], s10, v246
	v_cmp_gt_i32_e64 s[68:69], s10, v247
	v_cmp_le_i32_e32 vcc, s10, v246
	v_cndmask_b32_e64 v119, v3, v119, s[66:67]
	s_or_b64 s[66:67], s[66:67], s[68:69]
	v_cndmask_b32_e64 v118, v3, v118, s[66:67]
	s_or_b64 s[66:67], s[66:67], s[64:65]
	s_or_b64 s[64:65], s[68:69], s[64:65]
	v_cndmask_b32_e64 v117, v3, v117, s[66:67]
	s_or_b64 s[66:67], s[66:67], s[62:63]
	s_or_b64 s[62:63], s[64:65], s[62:63]
	v_cndmask_b32_e64 v116, v3, v116, s[66:67]
	s_or_b64 s[66:67], s[66:67], s[60:61]
	s_or_b64 s[60:61], s[62:63], s[60:61]
	v_cndmask_b32_e64 v115, v3, v115, s[66:67]
	s_or_b64 s[66:67], s[66:67], s[58:59]
	s_or_b64 s[58:59], s[60:61], s[58:59]
	v_cndmask_b32_e64 v114, v3, v114, s[66:67]
	s_or_b64 s[66:67], s[66:67], s[56:57]
	s_or_b64 s[56:57], s[58:59], s[56:57]
	v_cndmask_b32_e64 v113, v3, v113, s[66:67]
	s_or_b64 s[66:67], s[66:67], s[54:55]
	s_or_b64 s[54:55], s[56:57], s[54:55]
	v_cndmask_b32_e64 v112, v3, v112, s[66:67]
	s_or_b64 s[66:67], s[66:67], s[52:53]
	s_or_b64 s[52:53], s[54:55], s[52:53]
	v_cndmask_b32_e64 v123, v3, v123, s[66:67]
	s_or_b64 s[66:67], s[66:67], s[50:51]
	s_or_b64 s[50:51], s[52:53], s[50:51]
	v_cndmask_b32_e64 v122, v3, v122, s[66:67]
	s_or_b64 s[66:67], s[66:67], s[48:49]
	s_or_b64 s[48:49], s[50:51], s[48:49]
	v_cndmask_b32_e64 v121, v3, v121, s[66:67]
	s_or_b64 s[66:67], s[66:67], s[46:47]
	s_or_b64 s[46:47], s[48:49], s[46:47]
	v_cndmask_b32_e64 v120, v3, v120, s[66:67]
	s_or_b64 s[66:67], s[66:67], s[44:45]
	s_or_b64 s[44:45], s[46:47], s[44:45]
	v_cndmask_b32_e64 v127, v3, v127, s[66:67]
	s_or_b64 s[66:67], s[66:67], s[42:43]
	s_or_b64 s[42:43], s[44:45], s[42:43]
	v_cndmask_b32_e64 v126, v3, v126, s[66:67]
	s_or_b64 s[66:67], s[66:67], s[40:41]
	s_or_b64 s[40:41], s[42:43], s[40:41]
	v_cndmask_b32_e64 v125, v3, v125, s[66:67]
	s_or_b64 s[66:67], s[66:67], s[38:39]
	s_or_b64 s[38:39], s[40:41], s[38:39]
	v_cndmask_b32_e64 v130, v3, v130, s[68:69]
	v_cndmask_b32_e64 v124, v3, v124, s[66:67]
	v_cndmask_b32_e64 v129, v3, v129, s[64:65]
	v_cndmask_b32_e64 v128, v3, v128, s[62:63]
	v_cndmask_b32_e64 v103, v3, v103, s[60:61]
	v_cndmask_b32_e64 v102, v3, v102, s[58:59]
	v_cndmask_b32_e64 v101, v3, v101, s[56:57]
	v_cndmask_b32_e64 v100, v3, v100, s[54:55]
	v_cndmask_b32_e64 v111, v3, v111, s[52:53]
	v_cndmask_b32_e64 v110, v3, v110, s[50:51]
	v_cndmask_b32_e64 v109, v3, v109, s[48:49]
	v_cndmask_b32_e64 v108, v3, v108, s[46:47]
	v_cndmask_b32_e64 v107, v3, v107, s[44:45]
	v_cndmask_b32_e64 v106, v3, v106, s[42:43]
	v_cndmask_b32_e64 v105, v3, v105, s[40:41]
	v_cndmask_b32_e64 v104, v3, v104, s[38:39]
	s_and_saveexec_b64 s[30:31], vcc
	v_mov_b32_e32 v131, 0xff800000
	s_or_b64 exec, exec, s[30:31]
